# final w_down epilogue: the 16 residual loads prefetched through a 3-row-group register ring with counted waits (was one load + vmcnt(0) at a time, also waiting on each row's write-through ssq store)
# baseline (speedup 1.0000x reference)
; __device__ __forceinline__ f32x2 unpkh2(unsigned w) { return __builtin_convertvector(__builtin_bit_cast(f16x2_t, w), f32x2); }
;     __device__ __forceinline__ void operator()(f32x4 (&acc)[2][2][4][2], const pg8::Unit& u, int  , int wr, int wc, int fr, int fq) const {
;         const int j = u.pm < 32 ? 0 : 1;
;         const int colt = u.pn * 256 + wc * 32 + 8 * fq;
;         f32x4 gv[2][2];
; #pragma unroll
;         for (int bj = 0; bj < 2; ++bj)
; #pragma unroll
;             for (int n = 0; n < 2; ++n) gv[bj][n] = *(const f32x4*)(gate + (size_t)j * NMOD + colt + bj * 128 + 4 * n);
; #pragma unroll
;         for (int ai = 0; ai < 2; ++ai)
; #pragma unroll
;             for (int m = 0; m < 4; ++m) {
;                 const int row = u.pm * 256 + ai * 128 + wr * 64 + m * 16 + fr;
;                 const bf16_t* xrp = xr + (size_t)row * D + colt;
;                 float sq = 0.f;
; #pragma unroll
;                 for (int bj = 0; bj < 2; ++bj) {
;                     const u32x4 xw = *(const u32x4*)(xrp + bj * 128);
;                     const f32x2 h0 = unpkh2(xw.x), h1 = unpkh2(xw.y), h2 = unpkh2(xw.z), h3 = unpkh2(xw.w);
;                     const f32x4 x0 = (f32x4){h0.x, h0.y, h1.x, h1.y} + gv[bj][0] * acc[ai][bj][m][0], x1 = (f32x4){h2.x, h2.y, h3.x, h3.y} + gv[bj][1] * acc[ai][bj][m][1];
;                     acc[ai][bj][m][0] = x0; acc[ai][bj][m][1] = x1;
;                     sq += ((x0.x * x0.x + x0.y * x0.y) + (x0.z * x0.z + x0.w * x0.w)) + ((x1.x * x1.x + x1.y * x1.y) + (x1.z * x1.z + x1.w * x1.w));
;                 }
;                 sq += __shfl_xor(sq, 16); sq += __shfl_xor(sq, 32);
;                 if (fq == 0) __hip_atomic_store(ssq + (size_t)row * 16 + u.pn * 4 + wc, sq, RLX_AGENT);
;             }
.LBB0_2306:
	s_cmp_gt_i32 s78, 31
	s_cselect_b32 s11, 0x6000, 0
	v_lshl_or_b32 v160, s10, 8, v213
	s_add_u32 s66, s8, s11
	s_addc_u32 s67, s9, 0
	v_ashrrev_i32_e32 v161, 31, v160
	v_lshl_add_u32 v158, s78, 8, v211
	v_lshl_add_u64 v[46:47], v[160:161], 2, s[66:67]
	s_lshl_b32 s66, s10, 2
	v_ashrrev_i32_e32 v159, 31, v158
	v_readlane_b32 s10, v249, 51
	v_lshlrev_b64 v[162:163], 11, v[158:159]
	v_readlane_b32 s11, v249, 52
	global_load_dwordx4 v[66:69], v[46:47], off offset:16
	global_load_dwordx4 v[70:73], v[46:47], off
	global_load_dwordx4 v[42:45], v[46:47], off offset:528
	s_nop 0
	global_load_dwordx4 v[46:49], v[46:47], off offset:512
	v_lshl_add_u64 v[162:163], s[10:11], 0, v[162:163]
	v_lshl_add_u64 v[162:163], v[160:161], 1, v[162:163]
	v_mov_b32_e32 v146, v162
	v_mov_b32_e32 v147, v163
	global_load_dwordx4 v[232:235], v[162:163], off
	global_load_dwordx4 v[236:239], v[162:163], off offset:256
	s_mov_b32 s100, 0x8000
	s_mov_b32 s101, 0
	v_lshl_add_u64 v[156:157], v[146:147], 0, s[100:101]
	global_load_dwordx4 v[240:243], v[156:157], off
	global_load_dwordx4 v[244:247], v[156:157], off offset:256
	v_lshl_add_u64 v[156:157], v[156:157], 0, s[100:101]
	global_load_dwordx4 v[148:151], v[156:157], off
	global_load_dwordx4 v[152:155], v[156:157], off offset:256
	v_readlane_b32 s10, v249, 26
	v_readlane_b32 s11, v249, 27
	s_ashr_i32 s67, s66, 31
	s_waitcnt vmcnt(5)
	v_cvt_f32_f16_e32 v164, v232
	v_cvt_f32_f16_sdwa v165, v232 dst_sel:DWORD dst_unused:UNUSED_PAD src0_sel:WORD_1
	v_cvt_f32_f16_e32 v170, v233
	v_cvt_f32_f16_sdwa v171, v233 dst_sel:DWORD dst_unused:UNUSED_PAD src0_sel:WORD_1
	v_cvt_f32_f16_e32 v174, v234
	v_cvt_f32_f16_sdwa v175, v234 dst_sel:DWORD dst_unused:UNUSED_PAD src0_sel:WORD_1
	v_cvt_f32_f16_e32 v172, v235
	v_cvt_f32_f16_sdwa v173, v235 dst_sel:DWORD dst_unused:UNUSED_PAD src0_sel:WORD_1
	v_pk_fma_f32 v[144:145], v[144:145], v[72:73], v[170:171]
	v_pk_fma_f32 v[142:143], v[142:143], v[70:71], v[164:165]
	v_mul_f32_e32 v165, v145, v145
	v_mul_f32_e32 v164, v143, v143
	v_pk_fma_f32 v[140:141], v[140:141], v[68:69], v[172:173]
	v_pk_fma_f32 v[138:139], v[138:139], v[66:67], v[174:175]
	v_fmac_f32_e32 v164, v142, v142
	v_fmac_f32_e32 v165, v144, v144
	v_add_f32_e32 v164, v164, v165
	v_mul_f32_e32 v165, v139, v139
	v_mul_f32_e32 v170, v141, v141
	v_fmac_f32_e32 v165, v138, v138
	v_fmac_f32_e32 v170, v140, v140
	v_add_f32_e32 v165, v165, v170
	v_add_f32_e32 v174, v164, v165
	s_waitcnt vmcnt(4)
	v_cvt_f32_f16_e32 v162, v236
	v_cvt_f32_f16_sdwa v163, v236 dst_sel:DWORD dst_unused:UNUSED_PAD src0_sel:WORD_1
	v_cvt_f32_f16_e32 v164, v237
	v_cvt_f32_f16_sdwa v165, v237 dst_sel:DWORD dst_unused:UNUSED_PAD src0_sel:WORD_1
	v_cvt_f32_f16_e32 v170, v238
	v_cvt_f32_f16_sdwa v171, v238 dst_sel:DWORD dst_unused:UNUSED_PAD src0_sel:WORD_1
	v_cvt_f32_f16_e32 v172, v239
	v_cvt_f32_f16_sdwa v173, v239 dst_sel:DWORD dst_unused:UNUSED_PAD src0_sel:WORD_1
	v_pk_fma_f32 v[136:137], v[136:137], v[48:49], v[164:165]
	v_pk_fma_f32 v[134:135], v[134:135], v[46:47], v[162:163]
	v_mul_f32_e32 v163, v137, v137
	v_mul_f32_e32 v162, v135, v135
	v_pk_fma_f32 v[132:133], v[132:133], v[44:45], v[172:173]
	v_pk_fma_f32 v[130:131], v[130:131], v[42:43], v[170:171]
	v_fmac_f32_e32 v162, v134, v134
	v_fmac_f32_e32 v163, v136, v136
	v_add_f32_e32 v162, v162, v163
	v_mul_f32_e32 v163, v131, v131
	v_mul_f32_e32 v164, v133, v133
	v_fmac_f32_e32 v163, v130, v130
	v_fmac_f32_e32 v164, v132, v132
	v_add_f32_e32 v163, v163, v164
	v_add_f32_e32 v162, v162, v163
	v_add_f32_e32 v162, v174, v162
	ds_bpermute_b32 v163, v209, v162
	s_waitcnt lgkmcnt(0)
	v_add_f32_e32 v170, v162, v163
	ds_bpermute_b32 v171, v210, v170
	v_lshlrev_b64 v[162:163], 6, v[158:159]
	v_lshl_add_u64 v[172:173], s[10:11], 0, v[162:163]
	s_and_saveexec_b64 s[68:69], s[62:63]
	s_cbranch_execz .LBB0_2308
	v_lshl_add_u64 v[162:163], s[66:67], 2, v[172:173]
	s_lshl_b32 s28, s75, 2
	s_waitcnt lgkmcnt(0)
	v_add_f32_e32 v164, v170, v171
	v_lshl_add_u64 v[162:163], v[162:163], 0, s[28:29]
	global_store_dword v[162:163], v164, off sc1
.LBB0_2308:
	s_or_b64 exec, exec, s[68:69]
	s_mov_b32 s100, 0x18000
	s_mov_b32 s101, 0
	v_lshl_add_u64 v[156:157], v[146:147], 0, s[100:101]
	global_load_dwordx4 v[232:235], v[156:157], off
	global_load_dwordx4 v[236:239], v[156:157], off offset:256
	v_or_b32_e32 v170, 16, v158
	s_waitcnt lgkmcnt(0)
	v_ashrrev_i32_e32 v171, 31, v170
	v_readlane_b32 s10, v249, 51
	v_lshlrev_b64 v[162:163], 11, v[170:171]
	v_readlane_b32 s11, v249, 52
	s_nop 1
	v_lshl_add_u64 v[162:163], s[10:11], 0, v[162:163]
	v_lshl_add_u64 v[162:163], v[160:161], 1, v[162:163]
	v_readlane_b32 s10, v249, 26
	v_readlane_b32 s11, v249, 27
	s_waitcnt vmcnt(5)
	v_cvt_f32_f16_e32 v164, v240
	v_cvt_f32_f16_sdwa v165, v240 dst_sel:DWORD dst_unused:UNUSED_PAD src0_sel:WORD_1
	v_cvt_f32_f16_e32 v174, v241
	v_cvt_f32_f16_sdwa v175, v241 dst_sel:DWORD dst_unused:UNUSED_PAD src0_sel:WORD_1
	v_cvt_f32_f16_e32 v178, v242
	v_cvt_f32_f16_sdwa v179, v242 dst_sel:DWORD dst_unused:UNUSED_PAD src0_sel:WORD_1
	v_cvt_f32_f16_e32 v176, v243
	v_cvt_f32_f16_sdwa v177, v243 dst_sel:DWORD dst_unused:UNUSED_PAD src0_sel:WORD_1
	v_pk_fma_f32 v[128:129], v[128:129], v[72:73], v[174:175]
	v_pk_fma_f32 v[126:127], v[126:127], v[70:71], v[164:165]
	v_mul_f32_e32 v165, v129, v129
	v_mul_f32_e32 v164, v127, v127
	v_pk_fma_f32 v[124:125], v[124:125], v[68:69], v[176:177]
	v_pk_fma_f32 v[122:123], v[122:123], v[66:67], v[178:179]
	v_fmac_f32_e32 v164, v126, v126
	v_fmac_f32_e32 v165, v128, v128
	v_add_f32_e32 v164, v164, v165
	v_mul_f32_e32 v165, v123, v123
	v_mul_f32_e32 v174, v125, v125
	v_fmac_f32_e32 v165, v122, v122
	v_fmac_f32_e32 v174, v124, v124
	v_add_f32_e32 v165, v165, v174
	v_add_f32_e32 v178, v164, v165
	s_waitcnt vmcnt(4)
; __device__ __forceinline__ f32x2 unpkh2(unsigned w) { return __builtin_convertvector(__builtin_bit_cast(f16x2_t, w), f32x2); }
;     __device__ __forceinline__ void operator()(f32x4 (&acc)[2][2][4][2], const pg8::Unit& u, int  , int wr, int wc, int fr, int fq) const {
;     ...
;             for (int m = 0; m < 4; ++m) {
;                 const int row = u.pm * 256 + ai * 128 + wr * 64 + m * 16 + fr;
;                 const bf16_t* xrp = xr + (size_t)row * D + colt;
;                 float sq = 0.f;
; #pragma unroll
;                 for (int bj = 0; bj < 2; ++bj) {
;                     const u32x4 xw = *(const u32x4*)(xrp + bj * 128);
;                     const f32x2 h0 = unpkh2(xw.x), h1 = unpkh2(xw.y), h2 = unpkh2(xw.z), h3 = unpkh2(xw.w);
;                     const f32x4 x0 = (f32x4){h0.x, h0.y, h1.x, h1.y} + gv[bj][0] * acc[ai][bj][m][0], x1 = (f32x4){h2.x, h2.y, h3.x, h3.y} + gv[bj][1] * acc[ai][bj][m][1];
;                     acc[ai][bj][m][0] = x0; acc[ai][bj][m][1] = x1;
;                     sq += ((x0.x * x0.x + x0.y * x0.y) + (x0.z * x0.z + x0.w * x0.w)) + ((x1.x * x1.x + x1.y * x1.y) + (x1.z * x1.z + x1.w * x1.w));
;                 }
;                 sq += __shfl_xor(sq, 16); sq += __shfl_xor(sq, 32);
;                 if (fq == 0) __hip_atomic_store(ssq + (size_t)row * 16 + u.pn * 4 + wc, sq, RLX_AGENT);
;             }
	v_cvt_f32_f16_e32 v162, v244
	v_cvt_f32_f16_sdwa v163, v244 dst_sel:DWORD dst_unused:UNUSED_PAD src0_sel:WORD_1
	v_cvt_f32_f16_e32 v164, v245
	v_cvt_f32_f16_sdwa v165, v245 dst_sel:DWORD dst_unused:UNUSED_PAD src0_sel:WORD_1
	v_cvt_f32_f16_e32 v174, v246
	v_cvt_f32_f16_sdwa v175, v246 dst_sel:DWORD dst_unused:UNUSED_PAD src0_sel:WORD_1
	v_cvt_f32_f16_e32 v176, v247
	v_cvt_f32_f16_sdwa v177, v247 dst_sel:DWORD dst_unused:UNUSED_PAD src0_sel:WORD_1
	v_pk_fma_f32 v[120:121], v[120:121], v[48:49], v[164:165]
	v_pk_fma_f32 v[118:119], v[118:119], v[46:47], v[162:163]
	v_mul_f32_e32 v163, v121, v121
	v_mul_f32_e32 v162, v119, v119
	v_pk_fma_f32 v[116:117], v[116:117], v[44:45], v[176:177]
	v_pk_fma_f32 v[114:115], v[114:115], v[42:43], v[174:175]
	v_fmac_f32_e32 v162, v118, v118
	v_fmac_f32_e32 v163, v120, v120
	v_add_f32_e32 v162, v162, v163
	v_mul_f32_e32 v163, v115, v115
	v_mul_f32_e32 v164, v117, v117
	v_fmac_f32_e32 v163, v114, v114
	v_fmac_f32_e32 v164, v116, v116
	v_add_f32_e32 v163, v163, v164
	v_add_f32_e32 v162, v162, v163
	v_add_f32_e32 v162, v178, v162
	ds_bpermute_b32 v163, v209, v162
	s_waitcnt lgkmcnt(0)
	v_add_f32_e32 v174, v162, v163
	ds_bpermute_b32 v175, v210, v174
	v_lshlrev_b64 v[162:163], 6, v[170:171]
	v_lshl_add_u64 v[176:177], s[10:11], 0, v[162:163]
	s_and_saveexec_b64 s[68:69], s[62:63]
	s_cbranch_execz .LBB0_2310
	v_lshl_add_u64 v[162:163], s[66:67], 2, v[176:177]
	s_lshl_b32 s28, s75, 2
	s_waitcnt lgkmcnt(0)
	v_add_f32_e32 v164, v174, v175
	v_lshl_add_u64 v[162:163], v[162:163], 0, s[28:29]
	global_store_dword v[162:163], v164, off sc1
.LBB0_2310:
	s_or_b64 exec, exec, s[68:69]
	s_mov_b32 s100, 0x40000
	s_mov_b32 s101, 0
	v_lshl_add_u64 v[156:157], v[146:147], 0, s[100:101]
	global_load_dwordx4 v[240:243], v[156:157], off
	global_load_dwordx4 v[244:247], v[156:157], off offset:256
	v_or_b32_e32 v174, 32, v158
	s_waitcnt lgkmcnt(0)
	v_ashrrev_i32_e32 v175, 31, v174
	v_readlane_b32 s10, v249, 51
	v_lshlrev_b64 v[162:163], 11, v[174:175]
	v_readlane_b32 s11, v249, 52
	s_nop 1
	v_lshl_add_u64 v[162:163], s[10:11], 0, v[162:163]
	v_lshl_add_u64 v[162:163], v[160:161], 1, v[162:163]
	v_readlane_b32 s10, v249, 26
	v_readlane_b32 s11, v249, 27
	s_waitcnt vmcnt(5)
	v_cvt_f32_f16_e32 v164, v148
	v_cvt_f32_f16_sdwa v165, v148 dst_sel:DWORD dst_unused:UNUSED_PAD src0_sel:WORD_1
	v_cvt_f32_f16_e32 v178, v149
	v_cvt_f32_f16_sdwa v179, v149 dst_sel:DWORD dst_unused:UNUSED_PAD src0_sel:WORD_1
	v_cvt_f32_f16_e32 v182, v150
	v_cvt_f32_f16_sdwa v183, v150 dst_sel:DWORD dst_unused:UNUSED_PAD src0_sel:WORD_1
	v_cvt_f32_f16_e32 v180, v151
	v_cvt_f32_f16_sdwa v181, v151 dst_sel:DWORD dst_unused:UNUSED_PAD src0_sel:WORD_1
	v_pk_fma_f32 v[112:113], v[112:113], v[72:73], v[178:179]
	v_pk_fma_f32 v[110:111], v[110:111], v[70:71], v[164:165]
	v_mul_f32_e32 v165, v113, v113
	v_mul_f32_e32 v164, v111, v111
	v_pk_fma_f32 v[108:109], v[108:109], v[68:69], v[180:181]
	v_pk_fma_f32 v[106:107], v[106:107], v[66:67], v[182:183]
	v_fmac_f32_e32 v164, v110, v110
	v_fmac_f32_e32 v165, v112, v112
	v_add_f32_e32 v164, v164, v165
	v_mul_f32_e32 v165, v107, v107
	v_mul_f32_e32 v178, v109, v109
	v_fmac_f32_e32 v165, v106, v106
	v_fmac_f32_e32 v178, v108, v108
	v_add_f32_e32 v165, v165, v178
	v_add_f32_e32 v182, v164, v165
	s_waitcnt vmcnt(4)
	v_cvt_f32_f16_e32 v162, v152
	v_cvt_f32_f16_sdwa v163, v152 dst_sel:DWORD dst_unused:UNUSED_PAD src0_sel:WORD_1
	v_cvt_f32_f16_e32 v164, v153
	v_cvt_f32_f16_sdwa v165, v153 dst_sel:DWORD dst_unused:UNUSED_PAD src0_sel:WORD_1
	v_cvt_f32_f16_e32 v178, v154
	v_cvt_f32_f16_sdwa v179, v154 dst_sel:DWORD dst_unused:UNUSED_PAD src0_sel:WORD_1
	v_cvt_f32_f16_e32 v180, v155
	v_cvt_f32_f16_sdwa v181, v155 dst_sel:DWORD dst_unused:UNUSED_PAD src0_sel:WORD_1
	v_pk_fma_f32 v[104:105], v[104:105], v[48:49], v[164:165]
	v_pk_fma_f32 v[102:103], v[102:103], v[46:47], v[162:163]
	v_mul_f32_e32 v163, v105, v105
	v_mul_f32_e32 v162, v103, v103
	v_pk_fma_f32 v[100:101], v[100:101], v[44:45], v[180:181]
	v_pk_fma_f32 v[98:99], v[98:99], v[42:43], v[178:179]
	v_fmac_f32_e32 v162, v102, v102
	v_fmac_f32_e32 v163, v104, v104
	v_add_f32_e32 v162, v162, v163
	v_mul_f32_e32 v163, v99, v99
	v_mul_f32_e32 v164, v101, v101
	v_fmac_f32_e32 v163, v98, v98
	v_fmac_f32_e32 v164, v100, v100
	v_add_f32_e32 v163, v163, v164
	v_add_f32_e32 v162, v162, v163
	v_add_f32_e32 v162, v182, v162
	ds_bpermute_b32 v163, v209, v162
	s_waitcnt lgkmcnt(0)
	v_add_f32_e32 v178, v162, v163
	ds_bpermute_b32 v179, v210, v178
	v_lshlrev_b64 v[162:163], 6, v[174:175]
	v_lshl_add_u64 v[180:181], s[10:11], 0, v[162:163]
	s_and_saveexec_b64 s[68:69], s[62:63]
	s_cbranch_execz .LBB0_2312
	v_lshl_add_u64 v[162:163], s[66:67], 2, v[180:181]
	s_lshl_b32 s28, s75, 2
	s_waitcnt lgkmcnt(0)
	v_add_f32_e32 v164, v178, v179
	v_lshl_add_u64 v[162:163], v[162:163], 0, s[28:29]
	global_store_dword v[162:163], v164, off sc1
; __device__ __forceinline__ f32x2 unpkh2(unsigned w) { return __builtin_convertvector(__builtin_bit_cast(f16x2_t, w), f32x2); }
;     __device__ __forceinline__ void operator()(f32x4 (&acc)[2][2][4][2], const pg8::Unit& u, int  , int wr, int wc, int fr, int fq) const {
;     ...
;             for (int m = 0; m < 4; ++m) {
;                 const int row = u.pm * 256 + ai * 128 + wr * 64 + m * 16 + fr;
;                 const bf16_t* xrp = xr + (size_t)row * D + colt;
;                 float sq = 0.f;
; #pragma unroll
;                 for (int bj = 0; bj < 2; ++bj) {
;                     const u32x4 xw = *(const u32x4*)(xrp + bj * 128);
;                     const f32x2 h0 = unpkh2(xw.x), h1 = unpkh2(xw.y), h2 = unpkh2(xw.z), h3 = unpkh2(xw.w);
;                     const f32x4 x0 = (f32x4){h0.x, h0.y, h1.x, h1.y} + gv[bj][0] * acc[ai][bj][m][0], x1 = (f32x4){h2.x, h2.y, h3.x, h3.y} + gv[bj][1] * acc[ai][bj][m][1];
;                     acc[ai][bj][m][0] = x0; acc[ai][bj][m][1] = x1;
;                     sq += ((x0.x * x0.x + x0.y * x0.y) + (x0.z * x0.z + x0.w * x0.w)) + ((x1.x * x1.x + x1.y * x1.y) + (x1.z * x1.z + x1.w * x1.w));
;                 }
;                 sq += __shfl_xor(sq, 16); sq += __shfl_xor(sq, 32);
;                 if (fq == 0) __hip_atomic_store(ssq + (size_t)row * 16 + u.pn * 4 + wc, sq, RLX_AGENT);
;             }
.LBB0_2312:
	s_or_b64 exec, exec, s[68:69]
	s_mov_b32 s100, 0x48000
	s_mov_b32 s101, 0
	v_lshl_add_u64 v[156:157], v[146:147], 0, s[100:101]
	global_load_dwordx4 v[148:151], v[156:157], off
	global_load_dwordx4 v[152:155], v[156:157], off offset:256
	v_or_b32_e32 v178, 48, v158
	s_waitcnt lgkmcnt(0)
	v_ashrrev_i32_e32 v179, 31, v178
	v_readlane_b32 s10, v249, 51
	v_lshlrev_b64 v[162:163], 11, v[178:179]
	v_readlane_b32 s11, v249, 52
	s_nop 1
	v_lshl_add_u64 v[162:163], s[10:11], 0, v[162:163]
	v_lshl_add_u64 v[162:163], v[160:161], 1, v[162:163]
	v_readlane_b32 s10, v249, 26
	v_readlane_b32 s11, v249, 27
	s_waitcnt vmcnt(5)
	v_cvt_f32_f16_e32 v164, v232
	v_cvt_f32_f16_sdwa v165, v232 dst_sel:DWORD dst_unused:UNUSED_PAD src0_sel:WORD_1
	v_cvt_f32_f16_e32 v182, v233
	v_cvt_f32_f16_sdwa v183, v233 dst_sel:DWORD dst_unused:UNUSED_PAD src0_sel:WORD_1
	v_cvt_f32_f16_e32 v186, v234
	v_cvt_f32_f16_sdwa v187, v234 dst_sel:DWORD dst_unused:UNUSED_PAD src0_sel:WORD_1
	v_cvt_f32_f16_e32 v184, v235
	v_cvt_f32_f16_sdwa v185, v235 dst_sel:DWORD dst_unused:UNUSED_PAD src0_sel:WORD_1
	v_pk_fma_f32 v[96:97], v[96:97], v[72:73], v[182:183]
	v_pk_fma_f32 v[94:95], v[94:95], v[70:71], v[164:165]
	v_mul_f32_e32 v165, v97, v97
	v_mul_f32_e32 v164, v95, v95
	v_pk_fma_f32 v[92:93], v[92:93], v[68:69], v[184:185]
	v_pk_fma_f32 v[90:91], v[90:91], v[66:67], v[186:187]
	v_fmac_f32_e32 v164, v94, v94
	v_fmac_f32_e32 v165, v96, v96
	v_add_f32_e32 v164, v164, v165
	v_mul_f32_e32 v165, v91, v91
	v_mul_f32_e32 v182, v93, v93
	v_fmac_f32_e32 v165, v90, v90
	v_fmac_f32_e32 v182, v92, v92
	v_add_f32_e32 v165, v165, v182
	v_add_f32_e32 v186, v164, v165
	s_waitcnt vmcnt(4)
	v_cvt_f32_f16_e32 v162, v236
	v_cvt_f32_f16_sdwa v163, v236 dst_sel:DWORD dst_unused:UNUSED_PAD src0_sel:WORD_1
	v_cvt_f32_f16_e32 v164, v237
	v_cvt_f32_f16_sdwa v165, v237 dst_sel:DWORD dst_unused:UNUSED_PAD src0_sel:WORD_1
	v_cvt_f32_f16_e32 v182, v238
	v_cvt_f32_f16_sdwa v183, v238 dst_sel:DWORD dst_unused:UNUSED_PAD src0_sel:WORD_1
	v_cvt_f32_f16_e32 v184, v239
	v_cvt_f32_f16_sdwa v185, v239 dst_sel:DWORD dst_unused:UNUSED_PAD src0_sel:WORD_1
	v_pk_fma_f32 v[88:89], v[88:89], v[48:49], v[164:165]
	v_pk_fma_f32 v[86:87], v[86:87], v[46:47], v[162:163]
	v_mul_f32_e32 v163, v89, v89
	v_mul_f32_e32 v162, v87, v87
	v_pk_fma_f32 v[84:85], v[84:85], v[44:45], v[184:185]
	v_pk_fma_f32 v[82:83], v[82:83], v[42:43], v[182:183]
	v_fmac_f32_e32 v162, v86, v86
	v_fmac_f32_e32 v163, v88, v88
	v_add_f32_e32 v162, v162, v163
	v_mul_f32_e32 v163, v83, v83
	v_mul_f32_e32 v164, v85, v85
	v_fmac_f32_e32 v163, v82, v82
	v_fmac_f32_e32 v164, v84, v84
	v_add_f32_e32 v163, v163, v164
	v_add_f32_e32 v162, v162, v163
	v_add_f32_e32 v162, v186, v162
	ds_bpermute_b32 v163, v209, v162
	s_waitcnt lgkmcnt(0)
	v_add_f32_e32 v182, v162, v163
	ds_bpermute_b32 v183, v210, v182
	v_lshlrev_b64 v[162:163], 6, v[178:179]
	v_lshl_add_u64 v[184:185], s[10:11], 0, v[162:163]
	s_and_saveexec_b64 s[68:69], s[62:63]
	s_cbranch_execz .LBB0_2314
	v_lshl_add_u64 v[162:163], s[66:67], 2, v[184:185]
	s_lshl_b32 s28, s75, 2
	s_waitcnt lgkmcnt(0)
	v_add_f32_e32 v164, v182, v183
	v_lshl_add_u64 v[162:163], v[162:163], 0, s[28:29]
	global_store_dword v[162:163], v164, off sc1
.LBB0_2314:
	s_or_b64 exec, exec, s[68:69]
	s_mov_b32 s100, 0x50000
	s_mov_b32 s101, 0
	v_lshl_add_u64 v[156:157], v[146:147], 0, s[100:101]
	global_load_dwordx4 v[232:235], v[156:157], off
	global_load_dwordx4 v[236:239], v[156:157], off offset:256
	v_add_u32_e32 v182, 0x80, v158
	s_waitcnt lgkmcnt(0)
	v_ashrrev_i32_e32 v183, 31, v182
	v_readlane_b32 s10, v249, 51
	v_lshlrev_b64 v[162:163], 11, v[182:183]
	v_readlane_b32 s11, v249, 52
	s_nop 1
	v_lshl_add_u64 v[162:163], s[10:11], 0, v[162:163]
	v_lshl_add_u64 v[162:163], v[160:161], 1, v[162:163]
	v_readlane_b32 s10, v249, 26
	v_readlane_b32 s11, v249, 27
	s_waitcnt vmcnt(5)
	v_cvt_f32_f16_e32 v164, v240
	v_cvt_f32_f16_sdwa v165, v240 dst_sel:DWORD dst_unused:UNUSED_PAD src0_sel:WORD_1
	v_cvt_f32_f16_e32 v186, v241
	v_cvt_f32_f16_sdwa v187, v241 dst_sel:DWORD dst_unused:UNUSED_PAD src0_sel:WORD_1
	v_cvt_f32_f16_e32 v190, v242
	v_cvt_f32_f16_sdwa v191, v242 dst_sel:DWORD dst_unused:UNUSED_PAD src0_sel:WORD_1
	v_cvt_f32_f16_e32 v188, v243
	v_cvt_f32_f16_sdwa v189, v243 dst_sel:DWORD dst_unused:UNUSED_PAD src0_sel:WORD_1
	v_pk_fma_f32 v[80:81], v[80:81], v[72:73], v[186:187]
	v_pk_fma_f32 v[78:79], v[78:79], v[70:71], v[164:165]
	v_mul_f32_e32 v165, v81, v81
	v_mul_f32_e32 v164, v79, v79
	v_pk_fma_f32 v[76:77], v[76:77], v[68:69], v[188:189]
	v_pk_fma_f32 v[74:75], v[74:75], v[66:67], v[190:191]
	v_fmac_f32_e32 v164, v78, v78
	v_fmac_f32_e32 v165, v80, v80
	v_add_f32_e32 v164, v164, v165
	v_mul_f32_e32 v165, v75, v75
	v_mul_f32_e32 v186, v77, v77
	v_fmac_f32_e32 v165, v74, v74
	v_fmac_f32_e32 v186, v76, v76
	v_add_f32_e32 v165, v165, v186
	v_add_f32_e32 v190, v164, v165
	s_waitcnt vmcnt(4)
	v_cvt_f32_f16_e32 v162, v244
	v_cvt_f32_f16_sdwa v163, v244 dst_sel:DWORD dst_unused:UNUSED_PAD src0_sel:WORD_1
	v_cvt_f32_f16_e32 v164, v245
	v_cvt_f32_f16_sdwa v165, v245 dst_sel:DWORD dst_unused:UNUSED_PAD src0_sel:WORD_1
	v_cvt_f32_f16_e32 v186, v246
	v_cvt_f32_f16_sdwa v187, v246 dst_sel:DWORD dst_unused:UNUSED_PAD src0_sel:WORD_1
	v_cvt_f32_f16_e32 v188, v247
	v_cvt_f32_f16_sdwa v189, v247 dst_sel:DWORD dst_unused:UNUSED_PAD src0_sel:WORD_1
	v_pk_fma_f32 v[64:65], v[64:65], v[48:49], v[164:165]
	v_pk_fma_f32 v[62:63], v[62:63], v[46:47], v[162:163]
	v_mul_f32_e32 v163, v65, v65
	v_mul_f32_e32 v162, v63, v63
	v_pk_fma_f32 v[60:61], v[60:61], v[44:45], v[188:189]
	v_pk_fma_f32 v[58:59], v[58:59], v[42:43], v[186:187]
	v_fmac_f32_e32 v162, v62, v62
	v_fmac_f32_e32 v163, v64, v64
	v_add_f32_e32 v162, v162, v163
	v_mul_f32_e32 v163, v59, v59
	v_mul_f32_e32 v164, v61, v61
	v_fmac_f32_e32 v163, v58, v58
	v_fmac_f32_e32 v164, v60, v60
	v_add_f32_e32 v163, v163, v164
	v_add_f32_e32 v162, v162, v163
	v_add_f32_e32 v162, v190, v162
	ds_bpermute_b32 v163, v209, v162
	s_waitcnt lgkmcnt(0)
	v_add_f32_e32 v186, v162, v163
	ds_bpermute_b32 v187, v210, v186
	v_lshlrev_b64 v[162:163], 6, v[182:183]
	v_lshl_add_u64 v[188:189], s[10:11], 0, v[162:163]
	s_and_saveexec_b64 s[68:69], s[62:63]
	s_cbranch_execz .LBB0_2316
	v_lshl_add_u64 v[162:163], s[66:67], 2, v[188:189]
	s_lshl_b32 s28, s75, 2
	s_waitcnt lgkmcnt(0)
	v_add_f32_e32 v164, v186, v187
	v_lshl_add_u64 v[162:163], v[162:163], 0, s[28:29]
	global_store_dword v[162:163], v164, off sc1
; __device__ __forceinline__ f32x2 unpkh2(unsigned w) { return __builtin_convertvector(__builtin_bit_cast(f16x2_t, w), f32x2); }
;     __device__ __forceinline__ void operator()(f32x4 (&acc)[2][2][4][2], const pg8::Unit& u, int  , int wr, int wc, int fr, int fq) const {
;     ...
;             for (int m = 0; m < 4; ++m) {
;                 const int row = u.pm * 256 + ai * 128 + wr * 64 + m * 16 + fr;
;                 const bf16_t* xrp = xr + (size_t)row * D + colt;
;                 float sq = 0.f;
; #pragma unroll
;                 for (int bj = 0; bj < 2; ++bj) {
;                     const u32x4 xw = *(const u32x4*)(xrp + bj * 128);
;                     const f32x2 h0 = unpkh2(xw.x), h1 = unpkh2(xw.y), h2 = unpkh2(xw.z), h3 = unpkh2(xw.w);
;                     const f32x4 x0 = (f32x4){h0.x, h0.y, h1.x, h1.y} + gv[bj][0] * acc[ai][bj][m][0], x1 = (f32x4){h2.x, h2.y, h3.x, h3.y} + gv[bj][1] * acc[ai][bj][m][1];
;                     acc[ai][bj][m][0] = x0; acc[ai][bj][m][1] = x1;
;                     sq += ((x0.x * x0.x + x0.y * x0.y) + (x0.z * x0.z + x0.w * x0.w)) + ((x1.x * x1.x + x1.y * x1.y) + (x1.z * x1.z + x1.w * x1.w));
;                 }
;                 sq += __shfl_xor(sq, 16); sq += __shfl_xor(sq, 32);
;                 if (fq == 0) __hip_atomic_store(ssq + (size_t)row * 16 + u.pn * 4 + wc, sq, RLX_AGENT);
;             }
.LBB0_2316:
	s_or_b64 exec, exec, s[68:69]
	s_mov_b32 s100, 0x58000
	s_mov_b32 s101, 0
	v_lshl_add_u64 v[156:157], v[146:147], 0, s[100:101]
	global_load_dwordx4 v[240:243], v[156:157], off
	global_load_dwordx4 v[244:247], v[156:157], off offset:256
	v_add_u32_e32 v186, 0x90, v158
	s_waitcnt lgkmcnt(0)
	v_ashrrev_i32_e32 v187, 31, v186
	v_readlane_b32 s10, v249, 51
	v_lshlrev_b64 v[162:163], 11, v[186:187]
	v_readlane_b32 s11, v249, 52
	s_nop 1
	v_lshl_add_u64 v[162:163], s[10:11], 0, v[162:163]
	v_lshl_add_u64 v[162:163], v[160:161], 1, v[162:163]
	v_readlane_b32 s10, v249, 26
	v_readlane_b32 s11, v249, 27
	s_waitcnt vmcnt(5)
	v_cvt_f32_f16_e32 v164, v148
	v_cvt_f32_f16_sdwa v165, v148 dst_sel:DWORD dst_unused:UNUSED_PAD src0_sel:WORD_1
	v_cvt_f32_f16_e32 v190, v149
	v_cvt_f32_f16_sdwa v191, v149 dst_sel:DWORD dst_unused:UNUSED_PAD src0_sel:WORD_1
	v_cvt_f32_f16_e32 v194, v150
	v_cvt_f32_f16_sdwa v195, v150 dst_sel:DWORD dst_unused:UNUSED_PAD src0_sel:WORD_1
	v_cvt_f32_f16_e32 v192, v151
	v_cvt_f32_f16_sdwa v193, v151 dst_sel:DWORD dst_unused:UNUSED_PAD src0_sel:WORD_1
	v_pk_fma_f32 v[56:57], v[56:57], v[72:73], v[190:191]
	v_pk_fma_f32 v[54:55], v[54:55], v[70:71], v[164:165]
	v_mul_f32_e32 v165, v57, v57
	v_mul_f32_e32 v164, v55, v55
	v_pk_fma_f32 v[52:53], v[52:53], v[68:69], v[192:193]
	v_pk_fma_f32 v[50:51], v[50:51], v[66:67], v[194:195]
	v_fmac_f32_e32 v164, v54, v54
	v_fmac_f32_e32 v165, v56, v56
	v_add_f32_e32 v164, v164, v165
	v_mul_f32_e32 v165, v51, v51
	v_mul_f32_e32 v190, v53, v53
	v_fmac_f32_e32 v165, v50, v50
	v_fmac_f32_e32 v190, v52, v52
	v_add_f32_e32 v165, v165, v190
	v_add_f32_e32 v194, v164, v165
	s_waitcnt vmcnt(4)
	v_cvt_f32_f16_e32 v162, v152
	v_cvt_f32_f16_sdwa v163, v152 dst_sel:DWORD dst_unused:UNUSED_PAD src0_sel:WORD_1
	v_cvt_f32_f16_e32 v164, v153
	v_cvt_f32_f16_sdwa v165, v153 dst_sel:DWORD dst_unused:UNUSED_PAD src0_sel:WORD_1
	v_cvt_f32_f16_e32 v190, v154
	v_cvt_f32_f16_sdwa v191, v154 dst_sel:DWORD dst_unused:UNUSED_PAD src0_sel:WORD_1
	v_cvt_f32_f16_e32 v192, v155
	v_cvt_f32_f16_sdwa v193, v155 dst_sel:DWORD dst_unused:UNUSED_PAD src0_sel:WORD_1
	v_pk_fma_f32 v[40:41], v[40:41], v[48:49], v[164:165]
	v_pk_fma_f32 v[38:39], v[38:39], v[46:47], v[162:163]
	v_mul_f32_e32 v163, v41, v41
	v_mul_f32_e32 v162, v39, v39
	v_pk_fma_f32 v[36:37], v[36:37], v[44:45], v[192:193]
	v_pk_fma_f32 v[34:35], v[34:35], v[42:43], v[190:191]
	v_fmac_f32_e32 v162, v38, v38
	v_fmac_f32_e32 v163, v40, v40
	v_add_f32_e32 v162, v162, v163
	v_mul_f32_e32 v163, v35, v35
	v_mul_f32_e32 v164, v37, v37
	v_fmac_f32_e32 v163, v34, v34
	v_fmac_f32_e32 v164, v36, v36
	v_add_f32_e32 v163, v163, v164
	v_add_f32_e32 v162, v162, v163
	v_add_f32_e32 v162, v194, v162
	ds_bpermute_b32 v163, v209, v162
	s_waitcnt lgkmcnt(0)
	v_add_f32_e32 v190, v162, v163
	ds_bpermute_b32 v191, v210, v190
	v_lshlrev_b64 v[162:163], 6, v[186:187]
	v_lshl_add_u64 v[192:193], s[10:11], 0, v[162:163]
	s_and_saveexec_b64 s[68:69], s[62:63]
	s_cbranch_execz .LBB0_2318
	v_lshl_add_u64 v[162:163], s[66:67], 2, v[192:193]
	s_lshl_b32 s28, s75, 2
	s_waitcnt lgkmcnt(0)
	v_add_f32_e32 v164, v190, v191
	v_lshl_add_u64 v[162:163], v[162:163], 0, s[28:29]
	global_store_dword v[162:163], v164, off sc1
; __device__ __forceinline__ f32x2 unpkh2(unsigned w) { return __builtin_convertvector(__builtin_bit_cast(f16x2_t, w), f32x2); }
;     __device__ __forceinline__ void operator()(f32x4 (&acc)[2][2][4][2], const pg8::Unit& u, int  , int wr, int wc, int fr, int fq) const {
;     ...
;             for (int m = 0; m < 4; ++m) {
;                 const int row = u.pm * 256 + ai * 128 + wr * 64 + m * 16 + fr;
;                 const bf16_t* xrp = xr + (size_t)row * D + colt;
;                 float sq = 0.f;
; #pragma unroll
;                 for (int bj = 0; bj < 2; ++bj) {
;                     const u32x4 xw = *(const u32x4*)(xrp + bj * 128);
;                     const f32x2 h0 = unpkh2(xw.x), h1 = unpkh2(xw.y), h2 = unpkh2(xw.z), h3 = unpkh2(xw.w);
;                     const f32x4 x0 = (f32x4){h0.x, h0.y, h1.x, h1.y} + gv[bj][0] * acc[ai][bj][m][0], x1 = (f32x4){h2.x, h2.y, h3.x, h3.y} + gv[bj][1] * acc[ai][bj][m][1];
;                     acc[ai][bj][m][0] = x0; acc[ai][bj][m][1] = x1;
;                     sq += ((x0.x * x0.x + x0.y * x0.y) + (x0.z * x0.z + x0.w * x0.w)) + ((x1.x * x1.x + x1.y * x1.y) + (x1.z * x1.z + x1.w * x1.w));
;                 }
;                 sq += __shfl_xor(sq, 16); sq += __shfl_xor(sq, 32);
;                 if (fq == 0) __hip_atomic_store(ssq + (size_t)row * 16 + u.pn * 4 + wc, sq, RLX_AGENT);
;             }
.LBB0_2318:
	s_or_b64 exec, exec, s[68:69]
	v_add_u32_e32 v190, 0xa0, v158
	s_waitcnt lgkmcnt(0)
	v_ashrrev_i32_e32 v191, 31, v190
	v_readlane_b32 s10, v249, 51
	v_lshlrev_b64 v[162:163], 11, v[190:191]
	v_readlane_b32 s11, v249, 52
	s_nop 1
	v_lshl_add_u64 v[162:163], s[10:11], 0, v[162:163]
	v_lshl_add_u64 v[162:163], v[160:161], 1, v[162:163]
	v_readlane_b32 s10, v249, 26
	v_readlane_b32 s11, v249, 27
	s_waitcnt vmcnt(3)
	v_cvt_f32_f16_e32 v164, v232
	v_cvt_f32_f16_sdwa v165, v232 dst_sel:DWORD dst_unused:UNUSED_PAD src0_sel:WORD_1
	v_cvt_f32_f16_e32 v194, v233
	v_cvt_f32_f16_sdwa v195, v233 dst_sel:DWORD dst_unused:UNUSED_PAD src0_sel:WORD_1
	v_cvt_f32_f16_e32 v198, v234
	v_cvt_f32_f16_sdwa v199, v234 dst_sel:DWORD dst_unused:UNUSED_PAD src0_sel:WORD_1
	v_cvt_f32_f16_e32 v196, v235
	v_cvt_f32_f16_sdwa v197, v235 dst_sel:DWORD dst_unused:UNUSED_PAD src0_sel:WORD_1
	v_pk_fma_f32 v[32:33], v[32:33], v[72:73], v[194:195]
	v_pk_fma_f32 v[30:31], v[30:31], v[70:71], v[164:165]
	v_mul_f32_e32 v165, v33, v33
	v_mul_f32_e32 v164, v31, v31
	v_pk_fma_f32 v[28:29], v[28:29], v[68:69], v[196:197]
	v_pk_fma_f32 v[26:27], v[26:27], v[66:67], v[198:199]
	v_fmac_f32_e32 v164, v30, v30
	v_fmac_f32_e32 v165, v32, v32
	v_add_f32_e32 v164, v164, v165
	v_mul_f32_e32 v165, v27, v27
	v_mul_f32_e32 v194, v29, v29
	v_fmac_f32_e32 v165, v26, v26
	v_fmac_f32_e32 v194, v28, v28
	v_add_f32_e32 v165, v165, v194
	v_add_f32_e32 v202, v164, v165
	s_waitcnt vmcnt(2)
	v_cvt_f32_f16_e32 v162, v236
	v_cvt_f32_f16_sdwa v163, v236 dst_sel:DWORD dst_unused:UNUSED_PAD src0_sel:WORD_1
	v_cvt_f32_f16_e32 v164, v237
	v_cvt_f32_f16_sdwa v165, v237 dst_sel:DWORD dst_unused:UNUSED_PAD src0_sel:WORD_1
	v_cvt_f32_f16_e32 v194, v238
	v_cvt_f32_f16_sdwa v195, v238 dst_sel:DWORD dst_unused:UNUSED_PAD src0_sel:WORD_1
	v_cvt_f32_f16_e32 v200, v239
	v_cvt_f32_f16_sdwa v201, v239 dst_sel:DWORD dst_unused:UNUSED_PAD src0_sel:WORD_1
	v_pk_fma_f32 v[196:197], v[24:25], v[48:49], v[164:165]
	v_pk_fma_f32 v[198:199], v[22:23], v[46:47], v[162:163]
	v_pk_fma_f32 v[194:195], v[18:19], v[42:43], v[194:195]
	v_mul_f32_e32 v18, v199, v199
	v_mul_f32_e32 v19, v197, v197
	v_pk_fma_f32 v[22:23], v[20:21], v[44:45], v[200:201]
	v_fmac_f32_e32 v18, v198, v198
	v_fmac_f32_e32 v19, v196, v196
	v_add_f32_e32 v18, v18, v19
	v_mul_f32_e32 v19, v195, v195
	v_mul_f32_e32 v20, v23, v23
	v_fmac_f32_e32 v19, v194, v194
	v_fmac_f32_e32 v20, v22, v22
	v_add_f32_e32 v19, v19, v20
	v_add_f32_e32 v18, v18, v19
	v_add_f32_e32 v18, v202, v18
	ds_bpermute_b32 v19, v209, v18
	v_lshlrev_b64 v[20:21], 6, v[190:191]
	v_lshl_add_u64 v[202:203], s[10:11], 0, v[20:21]
	s_waitcnt lgkmcnt(0)
	v_add_f32_e32 v18, v18, v19
	ds_bpermute_b32 v19, v210, v18
	s_and_saveexec_b64 s[68:69], s[62:63]
	s_cbranch_execz .LBB0_2320
	s_waitcnt lgkmcnt(0)
	v_add_f32_e32 v20, v18, v19
	v_lshl_add_u64 v[18:19], s[66:67], 2, v[202:203]
	s_lshl_b32 s28, s75, 2
	v_lshl_add_u64 v[18:19], v[18:19], 0, s[28:29]
	global_store_dword v[18:19], v20, off sc1
.LBB0_2320:
	s_or_b64 exec, exec, s[68:69]
	v_add_u32_e32 v200, 0xb0, v158
	v_ashrrev_i32_e32 v201, 31, v200
	v_readlane_b32 s10, v249, 51
	s_waitcnt lgkmcnt(0)
	v_lshlrev_b64 v[18:19], 11, v[200:201]
	v_readlane_b32 s11, v249, 52
	s_nop 1
	v_lshl_add_u64 v[18:19], s[10:11], 0, v[18:19]
	v_lshl_add_u64 v[162:163], v[160:161], 1, v[18:19]
	v_readlane_b32 s10, v249, 26
	v_readlane_b32 s11, v249, 27
	s_waitcnt vmcnt(1)
	v_cvt_f32_f16_e32 v24, v240
	v_cvt_f32_f16_sdwa v25, v240 dst_sel:DWORD dst_unused:UNUSED_PAD src0_sel:WORD_1
	v_cvt_f32_f16_e32 v18, v241
	v_cvt_f32_f16_sdwa v19, v241 dst_sel:DWORD dst_unused:UNUSED_PAD src0_sel:WORD_1
	v_cvt_f32_f16_e32 v164, v242
	v_cvt_f32_f16_sdwa v165, v242 dst_sel:DWORD dst_unused:UNUSED_PAD src0_sel:WORD_1
	v_cvt_f32_f16_e32 v206, v243
	v_cvt_f32_f16_sdwa v207, v243 dst_sel:DWORD dst_unused:UNUSED_PAD src0_sel:WORD_1
	v_pk_fma_f32 v[20:21], v[16:17], v[72:73], v[18:19]
	v_pk_fma_f32 v[70:71], v[14:15], v[70:71], v[24:25]
	v_pk_fma_f32 v[24:25], v[10:11], v[66:67], v[164:165]
	v_mul_f32_e32 v10, v71, v71
	v_mul_f32_e32 v11, v21, v21
	v_pk_fma_f32 v[18:19], v[12:13], v[68:69], v[206:207]
	v_fmac_f32_e32 v10, v70, v70
	v_fmac_f32_e32 v11, v20, v20
	v_add_f32_e32 v10, v10, v11
	v_mul_f32_e32 v11, v25, v25
	v_mul_f32_e32 v12, v19, v19
	v_fmac_f32_e32 v11, v24, v24
	v_fmac_f32_e32 v12, v18, v18
	v_add_f32_e32 v11, v11, v12
	v_add_f32_e32 v66, v10, v11
	s_waitcnt vmcnt(0)
	v_cvt_f32_f16_e32 v14, v244
	v_cvt_f32_f16_sdwa v15, v244 dst_sel:DWORD dst_unused:UNUSED_PAD src0_sel:WORD_1
	v_cvt_f32_f16_e32 v10, v245
	v_cvt_f32_f16_sdwa v11, v245 dst_sel:DWORD dst_unused:UNUSED_PAD src0_sel:WORD_1
	v_cvt_f32_f16_e32 v16, v246
	v_cvt_f32_f16_sdwa v17, v246 dst_sel:DWORD dst_unused:UNUSED_PAD src0_sel:WORD_1
	v_cvt_f32_f16_e32 v12, v247
	v_cvt_f32_f16_sdwa v13, v247 dst_sel:DWORD dst_unused:UNUSED_PAD src0_sel:WORD_1
	v_pk_fma_f32 v[48:49], v[8:9], v[48:49], v[10:11]
	v_pk_fma_f32 v[46:47], v[6:7], v[46:47], v[14:15]
	v_pk_fma_f32 v[42:43], v[2:3], v[42:43], v[16:17]
	v_mul_f32_e32 v2, v47, v47
	v_mul_f32_e32 v3, v49, v49
	v_pk_fma_f32 v[44:45], v[4:5], v[44:45], v[12:13]
	v_fmac_f32_e32 v2, v46, v46
	v_fmac_f32_e32 v3, v48, v48
	v_add_f32_e32 v2, v2, v3
	v_mul_f32_e32 v3, v43, v43
	v_mul_f32_e32 v4, v45, v45
	v_fmac_f32_e32 v3, v42, v42
	v_fmac_f32_e32 v4, v44, v44
	v_add_f32_e32 v3, v3, v4
	v_add_f32_e32 v2, v2, v3
	v_add_f32_e32 v2, v66, v2
	ds_bpermute_b32 v3, v209, v2
	v_lshlrev_b64 v[4:5], 6, v[200:201]
	v_lshl_add_u64 v[66:67], s[10:11], 0, v[4:5]
	s_waitcnt lgkmcnt(0)
	v_add_f32_e32 v2, v2, v3
	ds_bpermute_b32 v3, v210, v2
	s_and_saveexec_b64 s[68:69], s[62:63]
	s_cbranch_execz .LBB0_2322
	s_waitcnt lgkmcnt(0)
	v_add_f32_e32 v4, v2, v3
	v_lshl_add_u64 v[2:3], s[66:67], 2, v[66:67]
	s_lshl_b32 s28, s75, 2
	v_lshl_add_u64 v[2:3], v[2:3], 0, s[28:29]
	global_store_dword v[2:3], v4, off sc1
